# P3 sample-row loads overlap the prompt rows; W_eff items redistributed (one per workgroup in P0, the rest in the idle part of the P2 tail)
# speedup vs baseline: 1.0316x; 1.0022x over previous
.LBB0_72:
	v_add_u32_e32 v50, 0, v17
	ds_read2_b32 v[46:47], v50 offset1:4
	v_add_u32_e32 v51, 0, v45
	v_add_u32_e32 v48, 0x10400, v51
	v_add_u32_e32 v49, 0x10440, v51
	v_add_u32_e32 v52, 0x10900, v51
	v_add_u32_e32 v53, 0x10940, v51
	v_add_u32_e32 v54, 0x10e00, v51
	v_add_u32_e32 v55, 0x10e40, v51
	v_add_u32_e32 v56, 0x11300, v51
	v_add_u32_e32 v57, 0x11340, v51
	ds_read_b32 v48, v48
	ds_read_b32 v49, v49
	ds_read_b32 v52, v52
	ds_read_b32 v53, v53
	ds_read_b32 v54, v54
	ds_read_b32 v55, v55
	ds_read_b32 v56, v56
	ds_read_b32 v57, v57
	s_waitcnt lgkmcnt(7)
	v_mfma_f32_16x16x4_f32 v[6:9], v46, v48, v[6:9]
	v_add_u32_e32 v58, 0x12700, v51
	s_add_i32 s4, s4, -8
	v_add_u32_e32 v17, 0x80, v17
	s_cmp_eq_u32 s4, 0
	v_add_u32_e32 v45, 0x2800, v45
	s_waitcnt lgkmcnt(6)
	v_mfma_f32_16x16x4_f32 v[2:5], v46, v49, v[2:5]
	ds_read2_b32 v[48:49], v50 offset0:16 offset1:20
	s_waitcnt lgkmcnt(6)
	v_mfma_f32_16x16x4_f32 v[6:9], v47, v52, v[6:9]
	v_add_u32_e32 v52, 0x11840, v51
	s_waitcnt lgkmcnt(5)
	v_mfma_f32_16x16x4_f32 v[2:5], v47, v53, v[2:5]
	ds_read2_b32 v[46:47], v50 offset0:8 offset1:12
	v_add_u32_e32 v53, 0x11d00, v51
	s_waitcnt lgkmcnt(0)
	v_mfma_f32_16x16x4_f32 v[6:9], v46, v54, v[6:9]
	v_add_u32_e32 v54, 0x11d40, v51
	v_mfma_f32_16x16x4_f32 v[2:5], v46, v55, v[2:5]
	v_add_u32_e32 v46, 0x11800, v51
	ds_read_b32 v46, v46
	v_add_u32_e32 v55, 0x12200, v51
	v_mfma_f32_16x16x4_f32 v[6:9], v47, v56, v[6:9]
	v_add_u32_e32 v56, 0x12240, v51
	v_add_u32_e32 v51, 0x12740, v51
	v_mfma_f32_16x16x4_f32 v[2:5], v47, v57, v[2:5]
	ds_read_b32 v47, v52
	ds_read_b32 v52, v53
	ds_read_b32 v53, v54
	ds_read_b32 v54, v55
	ds_read_b32 v55, v56
	ds_read_b32 v56, v58
	ds_read_b32 v51, v51
	s_waitcnt lgkmcnt(7)
	v_mfma_f32_16x16x4_f32 v[6:9], v48, v46, v[6:9]
	s_waitcnt lgkmcnt(6)
	v_mfma_f32_16x16x4_f32 v[2:5], v48, v47, v[2:5]
	ds_read2_b32 v[46:47], v50 offset0:24 offset1:28
	s_waitcnt lgkmcnt(6)
	v_mfma_f32_16x16x4_f32 v[6:9], v49, v52, v[6:9]
	s_waitcnt lgkmcnt(5)
	v_mfma_f32_16x16x4_f32 v[2:5], v49, v53, v[2:5]
	s_waitcnt lgkmcnt(0)
	v_mfma_f32_16x16x4_f32 v[6:9], v46, v54, v[6:9]
	v_mfma_f32_16x16x4_f32 v[2:5], v46, v55, v[2:5]
	v_mfma_f32_16x16x4_f32 v[6:9], v47, v56, v[6:9]
	v_mfma_f32_16x16x4_f32 v[2:5], v47, v51, v[2:5]
	s_cbranch_scc0 .LBB0_72
	s_mov_b32 s13, 1
	s_mov_b64 s[10:11], 0
	s_and_b64 vcc, exec, s[8:9]
	s_cbranch_vccz .LBB0_71
	s_and_b32 s4, s7, 0xc0
	s_ashr_i32 s7, s6, 31
	s_lshl_b64 s[6:7], s[6:7], 1
	s_add_u32 s6, s92, s6
	s_addc_u32 s7, s72, s7
	s_lshl_b32 s4, s4, 1
	s_add_u32 s6, s6, s4
	s_addc_u32 s7, s7, 0
	v_lshl_add_u64 v[18:19], s[6:7], 0, v[10:11]
	v_mov_b32_e32 v17, v11
	v_lshl_add_u64 v[18:19], v[18:19], 0, v[16:17]
	v_bfe_u32 v17, v6, 16, 1
	v_add3_u32 v6, v6, v17, s0
	v_bfe_u32 v17, v7, 16, 1
	v_lshrrev_b32_e32 v6, 16, v6
	v_add3_u32 v7, v7, v17, s0
	v_and_or_b32 v6, v7, s1, v6
	v_bfe_u32 v7, v8, 16, 1
	v_add3_u32 v7, v8, v7, s0
	v_bfe_u32 v8, v9, 16, 1
	v_or_b32_e32 v45, s12, v27
	v_lshrrev_b32_e32 v7, 16, v7
	v_add3_u32 v8, v9, v8, s0
	v_and_or_b32 v7, v8, s1, v7
	v_lshl_or_b32 v8, v45, 11, v44
	v_mov_b32_e32 v9, v11
	v_lshl_add_u64 v[8:9], v[18:19], 0, v[8:9]
	global_store_dwordx2 v[8:9], v[6:7], off
	v_bfe_u32 v6, v2, 16, 1
	v_add3_u32 v2, v2, v6, s0
	v_bfe_u32 v6, v3, 16, 1
	v_lshrrev_b32_e32 v2, 16, v2
	v_add3_u32 v3, v3, v6, s0
	v_and_or_b32 v2, v3, s1, v2
	v_bfe_u32 v3, v4, 16, 1
	v_add3_u32 v3, v4, v3, s0
	v_bfe_u32 v4, v5, 16, 1
	v_lshrrev_b32_e32 v3, 16, v3
	v_add3_u32 v4, v5, v4, s0
	v_and_or_b32 v3, v4, s1, v3
	v_add_co_u32_e32 v4, vcc, 0x8000, v8
	s_cmpk_gt_i32 s3, 0xff
	s_cselect_b32 s12, 1, 0
	s_cmpk_gt_i32 s2, 0x7f
	s_cselect_b32 s13, 1, 0
	s_or_b32 s12, s12, s13
	s_lshr_b32 s3, s2, 1
	s_add_i32 s3, s3, 0x100
	s_nop 0
	v_addc_co_u32_e32 v5, vcc, 0, v9, vcc
	s_cmp_lg_u32 s12, 0
	global_store_dwordx2 v[4:5], v[2:3], off
	s_barrier
	s_cbranch_scc0 .LBB0_70

.LBB0_124:
	v_add_u32_e32 v50, 0, v17
	ds_read2_b32 v[46:47], v50 offset1:4
	v_add_u32_e32 v51, 0, v45
	v_add_u32_e32 v48, 0x10400, v51
	v_add_u32_e32 v49, 0x10440, v51
	v_add_u32_e32 v52, 0x10900, v51
	v_add_u32_e32 v53, 0x10940, v51
	v_add_u32_e32 v54, 0x10e00, v51
	v_add_u32_e32 v55, 0x10e40, v51
	v_add_u32_e32 v56, 0x11300, v51
	v_add_u32_e32 v57, 0x11340, v51
	ds_read_b32 v48, v48
	ds_read_b32 v49, v49
	ds_read_b32 v52, v52
	ds_read_b32 v53, v53
	ds_read_b32 v54, v54
	ds_read_b32 v55, v55
	ds_read_b32 v56, v56
	ds_read_b32 v57, v57
	s_waitcnt lgkmcnt(7)
	v_mfma_f32_16x16x4_f32 v[6:9], v46, v48, v[6:9]
	v_add_u32_e32 v58, 0x12700, v51
	s_add_i32 s4, s4, -8
	v_add_u32_e32 v17, 0x80, v17
	s_cmp_eq_u32 s4, 0
	v_add_u32_e32 v45, 0x2800, v45
	s_waitcnt lgkmcnt(6)
	v_mfma_f32_16x16x4_f32 v[2:5], v46, v49, v[2:5]
	ds_read2_b32 v[48:49], v50 offset0:16 offset1:20
	s_waitcnt lgkmcnt(6)
	v_mfma_f32_16x16x4_f32 v[6:9], v47, v52, v[6:9]
	v_add_u32_e32 v52, 0x11840, v51
	s_waitcnt lgkmcnt(5)
	v_mfma_f32_16x16x4_f32 v[2:5], v47, v53, v[2:5]
	ds_read2_b32 v[46:47], v50 offset0:8 offset1:12
	v_add_u32_e32 v53, 0x11d00, v51
	s_waitcnt lgkmcnt(0)
	v_mfma_f32_16x16x4_f32 v[6:9], v46, v54, v[6:9]
	v_add_u32_e32 v54, 0x11d40, v51
	v_mfma_f32_16x16x4_f32 v[2:5], v46, v55, v[2:5]
	v_add_u32_e32 v46, 0x11800, v51
	ds_read_b32 v46, v46
	v_add_u32_e32 v55, 0x12200, v51
	v_mfma_f32_16x16x4_f32 v[6:9], v47, v56, v[6:9]
	v_add_u32_e32 v56, 0x12240, v51
	v_add_u32_e32 v51, 0x12740, v51
	v_mfma_f32_16x16x4_f32 v[2:5], v47, v57, v[2:5]
	ds_read_b32 v47, v52
	ds_read_b32 v52, v53
	ds_read_b32 v53, v54
	ds_read_b32 v54, v55
	ds_read_b32 v55, v56
	ds_read_b32 v56, v58
	ds_read_b32 v51, v51
	s_waitcnt lgkmcnt(7)
	v_mfma_f32_16x16x4_f32 v[6:9], v48, v46, v[6:9]
	s_waitcnt lgkmcnt(6)
	v_mfma_f32_16x16x4_f32 v[2:5], v48, v47, v[2:5]
	ds_read2_b32 v[46:47], v50 offset0:24 offset1:28
	s_waitcnt lgkmcnt(6)
	v_mfma_f32_16x16x4_f32 v[6:9], v49, v52, v[6:9]
	s_waitcnt lgkmcnt(5)
	v_mfma_f32_16x16x4_f32 v[2:5], v49, v53, v[2:5]
	s_waitcnt lgkmcnt(0)
	v_mfma_f32_16x16x4_f32 v[6:9], v46, v54, v[6:9]
	v_mfma_f32_16x16x4_f32 v[2:5], v46, v55, v[2:5]
	v_mfma_f32_16x16x4_f32 v[6:9], v47, v56, v[6:9]
	v_mfma_f32_16x16x4_f32 v[2:5], v47, v51, v[2:5]
	s_cbranch_scc0 .LBB0_124
	s_mov_b32 s13, 1
	s_mov_b64 s[10:11], 0
	s_and_b64 vcc, exec, s[8:9]
	s_cbranch_vccz .LBB0_123
	s_and_b32 s4, s7, 0xc0
	s_ashr_i32 s7, s6, 31
	s_lshl_b64 s[6:7], s[6:7], 1
	s_add_u32 s6, s92, s6
	s_addc_u32 s7, s72, s7
	s_lshl_b32 s4, s4, 1
	s_add_u32 s6, s6, s4
	s_addc_u32 s7, s7, 0
	v_lshl_add_u64 v[18:19], s[6:7], 0, v[10:11]
	v_mov_b32_e32 v17, v11
	v_lshl_add_u64 v[18:19], v[18:19], 0, v[16:17]
	v_bfe_u32 v17, v6, 16, 1
	v_add3_u32 v6, v6, v17, s0
	v_bfe_u32 v17, v7, 16, 1
	v_lshrrev_b32_e32 v6, 16, v6
	v_add3_u32 v7, v7, v17, s0
	v_and_or_b32 v6, v7, s1, v6
	v_bfe_u32 v7, v8, 16, 1
	v_add3_u32 v7, v8, v7, s0
	v_bfe_u32 v8, v9, 16, 1
	v_or_b32_e32 v45, s12, v27
	v_lshrrev_b32_e32 v7, 16, v7
	v_add3_u32 v8, v9, v8, s0
	v_and_or_b32 v7, v8, s1, v7
	v_lshl_or_b32 v8, v45, 11, v44
	v_mov_b32_e32 v9, v11
	v_lshl_add_u64 v[8:9], v[18:19], 0, v[8:9]
	global_store_dwordx2 v[8:9], v[6:7], off
	v_bfe_u32 v6, v2, 16, 1
	v_add3_u32 v2, v2, v6, s0
	v_bfe_u32 v6, v3, 16, 1
	v_lshrrev_b32_e32 v2, 16, v2
	v_add3_u32 v3, v3, v6, s0
	v_and_or_b32 v2, v3, s1, v2
	v_bfe_u32 v3, v4, 16, 1
	v_add3_u32 v3, v4, v3, s0
	v_bfe_u32 v4, v5, 16, 1
	v_lshrrev_b32_e32 v3, 16, v3
	v_add3_u32 v4, v5, v4, s0
	v_and_or_b32 v3, v4, s1, v3
	v_add_co_u32_e32 v4, vcc, 0x8000, v8
	s_add_i32 s3, s3, s96
	s_nop 0
	v_addc_co_u32_e32 v5, vcc, 0, v9, vcc
	s_cmpk_gt_i32 s3, 0xff
	global_store_dwordx2 v[4:5], v[2:3], off
	s_barrier
	s_cbranch_scc0 .LBB0_122

.Lp2_weff:
	s_waitcnt lgkmcnt(0)
	s_barrier
	v_readlane_b32 s0, v255, 0
	v_readlane_b32 s1, v255, 1
	s_sub_u32 s0, s0, 0xc8
	s_subb_u32 s1, s1, 0
	s_load_dwordx2 s[88:89], s[0:1], 0x48
	s_load_dwordx2 s[90:91], s[0:1], 0x50
	s_load_dwordx2 s[94:95], s[0:1], 0x60
	s_waitcnt lgkmcnt(0)
	v_or_b32_e32 v8, 0xa00, v0
	v_lshrrev_b32_e32 v28, 6, v8
	v_or_b32_e32 v8, 0xe00, v0
	v_lshrrev_b32_e32 v30, 6, v8
	v_lshrrev_b32_e32 v8, 5, v0
	v_lshlrev_b32_e32 v6, 4, v0
	v_or_b32_e32 v15, 0x600, v0
	v_and_b32_e32 v16, 2, v8
	v_lshrrev_b32_e32 v8, 3, v0
	v_and_b32_e32 v14, 0x3f0, v6
	v_or_b32_e32 v7, 0x200, v0
	v_or_b32_e32 v10, 0x400, v0
	v_lshrrev_b32_e32 v26, 6, v15
	v_and_b32_e32 v31, 15, v0
	s_add_i32 s0, 0, 0x10400
	v_and_b32_e32 v6, 0xf0, v6
	v_and_b32_e32 v8, 48, v8
	v_lshrrev_b32_e32 v35, 4, v15
	v_mov_b32_e32 v15, 0
	v_lshrrev_b32_e32 v4, 6, v0
	v_lshrrev_b32_e32 v24, 6, v7
	v_lshrrev_b32_e32 v25, 6, v10
	v_lshrrev_b32_e32 v32, 4, v0
	v_bfe_u32 v23, v0, 4, 2
	v_add_u32_e32 v47, s0, v6
	v_or_b32_e32 v17, v8, v31
	v_lshlrev_b32_e32 v37, 6, v16
	s_movk_i32 s0, 0x140
	v_lshrrev_b32_e32 v33, 4, v7
	v_lshrrev_b32_e32 v34, 4, v10
	v_mov_b32_e32 v7, v15
	v_add_u32_e32 v9, 0, v14
	v_mul_u32_u24_e32 v11, 0x410, v4
	v_mul_u32_u24_e32 v12, 0x410, v24
	v_mul_u32_u24_e32 v13, 0x410, v25
	v_mul_u32_u24_e32 v20, 0x410, v26
	v_mul_u32_u24_e32 v21, 0x410, v28
	v_mul_u32_u24_e32 v22, 0x410, v30
	v_mul_u32_u24_e32 v36, 0x410, v17
	v_mul_u32_u24_e32 v44, 0x140, v32
	v_mul_u32_u24_e32 v45, 0x140, v33
	v_mul_u32_u24_e32 v46, 0x140, v34
	v_mul_u32_u24_e32 v48, 0x140, v35
	v_lshlrev_b32_e32 v10, 2, v23
	v_lshlrev_b32_e32 v49, 14, v16
	v_lshl_add_u64 v[18:19], s[94:95], 0, v[6:7]
	v_mad_u32_u24 v6, v23, s0, v37
	s_mov_b32 s5, 0
	v_or_b32_e32 v27, 32, v4
	v_or_b32_e32 v29, 48, v4
	v_lshl_add_u64 v[16:17], s[88:89], 0, v[14:15]
	v_or_b32_e32 v36, v36, v10
	v_lshl_or_b32 v37, v31, 2, v6
	v_add_u32_e32 v38, v9, v11
	v_add_u32_e32 v39, v9, v12
	v_add_u32_e32 v40, v9, v13
	v_add_u32_e32 v41, v9, v20
	v_add_u32_e32 v42, v9, v21
	v_add_u32_e32 v43, v9, v22
	v_add_u32_e32 v44, v47, v44
	v_add_u32_e32 v45, v47, v45
	v_add_u32_e32 v46, v47, v46
	v_add_u32_e32 v47, v47, v48
	v_lshlrev_b32_e32 v14, 1, v8
	v_lshlrev_b32_e32 v20, 1, v10
	s_movk_i32 s0, 0x7fff
	s_mov_b32 s1, 0xffff0000
	v_lshlrev_b32_e32 v48, 1, v49
	s_add_i32 s3, s2, 0x100
.Lp2w_122:
	s_lshl_b32 s61, s3, 1
	s_and_b32 s4, s61, 0xffffffc0
	v_or_b32_e32 v6, s4, v4
	v_ashrrev_i32_e32 v7, 31, v6
	v_or_b32_e32 v8, s4, v24
	v_lshlrev_b64 v[6:7], 10, v[6:7]
	v_ashrrev_i32_e32 v9, 31, v8
	v_lshl_add_u64 v[6:7], v[16:17], 0, v[6:7]
	v_lshlrev_b64 v[8:9], 10, v[8:9]
	v_lshl_add_u64 v[8:9], v[16:17], 0, v[8:9]
	global_load_dwordx4 v[50:53], v[6:7], off
	global_load_dwordx4 v[54:57], v[8:9], off
	v_or_b32_e32 v6, s4, v25
	v_ashrrev_i32_e32 v7, 31, v6
	v_or_b32_e32 v8, s4, v26
	v_lshlrev_b64 v[6:7], 10, v[6:7]
	v_ashrrev_i32_e32 v9, 31, v8
	v_lshl_add_u64 v[6:7], v[16:17], 0, v[6:7]
	v_lshlrev_b64 v[8:9], 10, v[8:9]
	v_lshl_add_u64 v[8:9], v[16:17], 0, v[8:9]
	global_load_dwordx4 v[58:61], v[6:7], off
	global_load_dwordx4 v[62:65], v[8:9], off
	v_or_b32_e32 v6, s4, v27
	v_ashrrev_i32_e32 v7, 31, v6
	v_or_b32_e32 v8, s4, v28
	v_lshlrev_b64 v[6:7], 10, v[6:7]
	v_ashrrev_i32_e32 v9, 31, v8
	v_lshl_add_u64 v[6:7], v[16:17], 0, v[6:7]
	v_lshlrev_b64 v[8:9], 10, v[8:9]
	v_lshl_add_u64 v[8:9], v[16:17], 0, v[8:9]
	global_load_dwordx4 v[66:69], v[6:7], off
	global_load_dwordx4 v[94:97], v[8:9], off
	v_or_b32_e32 v6, s4, v29
	v_ashrrev_i32_e32 v7, 31, v6
	v_or_b32_e32 v8, s4, v30
	v_lshlrev_b64 v[6:7], 10, v[6:7]
	v_ashrrev_i32_e32 v9, 31, v8
	v_lshl_add_u64 v[6:7], v[16:17], 0, v[6:7]
	v_lshlrev_b64 v[8:9], 10, v[8:9]
	v_lshl_add_u64 v[8:9], v[16:17], 0, v[8:9]
	global_load_dwordx4 v[98:101], v[6:7], off
	global_load_dwordx4 v[102:105], v[8:9], off
	s_lshl_b32 s4, s3, 6
	s_and_b32 s12, s4, 0x7c0
	s_lshl_b32 s4, s12, 2
	s_mov_b64 s[10:11], -1
	s_mov_b32 s13, 0
	v_mov_b32_e32 v10, 0
	v_mov_b32_e32 v11, v15
	v_mov_b32_e32 v12, v15
	v_mov_b32_e32 v13, v15
	v_mov_b32_e32 v6, 0
	v_mov_b32_e32 v7, v15
	v_mov_b32_e32 v8, v15
	s_and_b32 s60, s61, 0xffffff00
	v_lshl_add_u64 v[22:23], v[18:19], 0, s[4:5]
	v_mov_b32_e32 v9, v15
	s_waitcnt vmcnt(7)
	ds_write_b128 v38, v[50:53]
	s_waitcnt vmcnt(6)
	ds_write_b128 v39, v[54:57]
	s_waitcnt vmcnt(5)
	ds_write_b128 v40, v[58:61]
	s_waitcnt vmcnt(4)
	ds_write_b128 v41, v[62:65]
	s_waitcnt vmcnt(3)
	ds_write_b128 v38, v[66:69] offset:33280
	s_waitcnt vmcnt(2)
	ds_write_b128 v42, v[94:97]
	s_waitcnt vmcnt(1)
	ds_write_b128 v38, v[98:101] offset:49920
	s_waitcnt vmcnt(0)
	ds_write_b128 v43, v[102:105]
.Lp2w_123:
	s_lshl_b32 s4, s13, 7
	s_or_b32 s4, s4, s60
	v_or_b32_e32 v50, s4, v32
	v_ashrrev_i32_e32 v51, 31, v50
	v_or_b32_e32 v54, s4, v33
	v_or_b32_e32 v58, s4, v34
	v_add_u32_e32 v62, s4, v35
	v_lshl_add_u64 v[52:53], v[50:51], 2, s[90:91]
	v_lshlrev_b64 v[50:51], 13, v[50:51]
	v_ashrrev_i32_e32 v55, 31, v54
	v_ashrrev_i32_e32 v59, 31, v58
	v_ashrrev_i32_e32 v63, 31, v62
	v_lshl_add_u64 v[50:51], v[22:23], 0, v[50:51]
	v_lshl_add_u64 v[56:57], v[54:55], 2, s[90:91]
	v_lshlrev_b64 v[54:55], 13, v[54:55]
	v_lshl_add_u64 v[60:61], v[58:59], 2, s[90:91]
	v_lshlrev_b64 v[58:59], 13, v[58:59]
	v_lshl_add_u64 v[64:65], v[62:63], 2, s[90:91]
	v_lshlrev_b64 v[62:63], 13, v[62:63]
	s_waitcnt lgkmcnt(0)
	s_barrier
	global_load_dword v66, v[52:53], off
	global_load_dword v68, v[56:57], off
	v_lshl_add_u64 v[54:55], v[22:23], 0, v[54:55]
	global_load_dwordx4 v[50:53], v[50:51], off
	v_lshl_add_u64 v[58:59], v[22:23], 0, v[58:59]
	v_lshl_add_u64 v[62:63], v[22:23], 0, v[62:63]
	global_load_dwordx4 v[54:57], v[54:55], off
	s_xor_b64 s[62:63], s[10:11], -1
	global_load_dword v94, v[60:61], off
	global_load_dword v96, v[64:65], off
	v_lshl_add_u32 v21, s13, 9, v36
	global_load_dwordx4 v[58:61], v[58:59], off
	s_mov_b32 s4, 32
	global_load_dwordx4 v[62:65], v[62:63], off
	v_mov_b32_e32 v49, v37
	s_waitcnt vmcnt(5)
	v_pk_mul_f32 v[50:51], v[50:51], v[66:67] op_sel_hi:[1,0]
	v_pk_mul_f32 v[52:53], v[52:53], v[66:67] op_sel_hi:[1,0]
	s_waitcnt vmcnt(4)
	v_pk_mul_f32 v[54:55], v[54:55], v[68:69] op_sel_hi:[1,0]
	v_pk_mul_f32 v[56:57], v[56:57], v[68:69] op_sel_hi:[1,0]
	s_waitcnt vmcnt(1)
	v_pk_mul_f32 v[58:59], v[58:59], v[94:95] op_sel_hi:[1,0]
	v_pk_mul_f32 v[60:61], v[60:61], v[94:95] op_sel_hi:[1,0]
	s_waitcnt vmcnt(0)
	v_pk_mul_f32 v[62:63], v[62:63], v[96:97] op_sel_hi:[1,0]
	v_pk_mul_f32 v[64:65], v[64:65], v[96:97] op_sel_hi:[1,0]
	ds_write_b128 v44, v[50:53]
	ds_write_b128 v45, v[54:57]
	ds_write_b128 v46, v[58:61]
	ds_write_b128 v47, v[62:65]
	s_waitcnt lgkmcnt(0)
	s_barrier
.Lp2w_124:
	v_add_u32_e32 v54, 0, v21
	ds_read2_b32 v[50:51], v54 offset1:4
	v_add_u32_e32 v55, 0, v49
	v_add_u32_e32 v52, 0x10400, v55
	v_add_u32_e32 v53, 0x10440, v55
	v_add_u32_e32 v56, 0x10900, v55
	v_add_u32_e32 v57, 0x10940, v55
	v_add_u32_e32 v58, 0x10e00, v55
	v_add_u32_e32 v59, 0x10e40, v55
	v_add_u32_e32 v60, 0x11300, v55
	v_add_u32_e32 v61, 0x11340, v55
	ds_read_b32 v52, v52
	ds_read_b32 v53, v53
	ds_read_b32 v56, v56
	ds_read_b32 v57, v57
	ds_read_b32 v58, v58
	ds_read_b32 v59, v59
	ds_read_b32 v60, v60
	ds_read_b32 v61, v61
	s_waitcnt lgkmcnt(7)
	v_mfma_f32_16x16x4_f32 v[10:13], v50, v52, v[10:13]
	v_add_u32_e32 v62, 0x12700, v55
	s_add_i32 s4, s4, -8
	v_add_u32_e32 v21, 0x80, v21
	s_cmp_eq_u32 s4, 0
	v_add_u32_e32 v49, 0x2800, v49
	s_waitcnt lgkmcnt(6)
	v_mfma_f32_16x16x4_f32 v[6:9], v50, v53, v[6:9]
	ds_read2_b32 v[52:53], v54 offset0:16 offset1:20
	s_waitcnt lgkmcnt(6)
	v_mfma_f32_16x16x4_f32 v[10:13], v51, v56, v[10:13]
	v_add_u32_e32 v56, 0x11840, v55
	s_waitcnt lgkmcnt(5)
	v_mfma_f32_16x16x4_f32 v[6:9], v51, v57, v[6:9]
	ds_read2_b32 v[50:51], v54 offset0:8 offset1:12
	v_add_u32_e32 v57, 0x11d00, v55
	s_waitcnt lgkmcnt(0)
	v_mfma_f32_16x16x4_f32 v[10:13], v50, v58, v[10:13]
	v_add_u32_e32 v58, 0x11d40, v55
	v_mfma_f32_16x16x4_f32 v[6:9], v50, v59, v[6:9]
	v_add_u32_e32 v50, 0x11800, v55
	ds_read_b32 v50, v50
	v_add_u32_e32 v59, 0x12200, v55
	v_mfma_f32_16x16x4_f32 v[10:13], v51, v60, v[10:13]
	v_add_u32_e32 v60, 0x12240, v55
	v_add_u32_e32 v55, 0x12740, v55
	v_mfma_f32_16x16x4_f32 v[6:9], v51, v61, v[6:9]
	ds_read_b32 v51, v56
	ds_read_b32 v56, v57
	ds_read_b32 v57, v58
	ds_read_b32 v58, v59
	ds_read_b32 v59, v60
	ds_read_b32 v60, v62
	ds_read_b32 v55, v55
	s_waitcnt lgkmcnt(7)
	v_mfma_f32_16x16x4_f32 v[10:13], v52, v50, v[10:13]
	s_waitcnt lgkmcnt(6)
	v_mfma_f32_16x16x4_f32 v[6:9], v52, v51, v[6:9]
	ds_read2_b32 v[50:51], v54 offset0:24 offset1:28
	s_waitcnt lgkmcnt(6)
	v_mfma_f32_16x16x4_f32 v[10:13], v53, v56, v[10:13]
	s_waitcnt lgkmcnt(5)
	v_mfma_f32_16x16x4_f32 v[6:9], v53, v57, v[6:9]
	s_waitcnt lgkmcnt(0)
	v_mfma_f32_16x16x4_f32 v[10:13], v50, v58, v[10:13]
	v_mfma_f32_16x16x4_f32 v[6:9], v50, v59, v[6:9]
	v_mfma_f32_16x16x4_f32 v[10:13], v51, v60, v[10:13]
	v_mfma_f32_16x16x4_f32 v[6:9], v51, v55, v[6:9]
	s_cbranch_scc0 .Lp2w_124
	s_mov_b32 s13, 1
	s_mov_b64 s[10:11], 0
	s_and_b64 vcc, exec, s[62:63]
	s_cbranch_vccz .Lp2w_123
	s_and_b32 s4, s61, 0xc0
	s_ashr_i32 s61, s60, 31
	s_lshl_b64 s[60:61], s[60:61], 1
	s_add_u32 s60, s92, s60
	s_addc_u32 s61, s72, s61
	s_lshl_b32 s4, s4, 1
	s_add_u32 s60, s60, s4
	s_addc_u32 s61, s61, 0
	v_lshl_add_u64 v[22:23], s[60:61], 0, v[14:15]
	v_mov_b32_e32 v21, v15
	v_lshl_add_u64 v[22:23], v[22:23], 0, v[20:21]
	v_bfe_u32 v21, v10, 16, 1
	v_add3_u32 v10, v10, v21, s0
	v_bfe_u32 v21, v11, 16, 1
	v_lshrrev_b32_e32 v10, 16, v10
	v_add3_u32 v11, v11, v21, s0
	v_and_or_b32 v10, v11, s1, v10
	v_bfe_u32 v11, v12, 16, 1
	v_add3_u32 v11, v12, v11, s0
	v_bfe_u32 v12, v13, 16, 1
	v_or_b32_e32 v49, s12, v31
	v_lshrrev_b32_e32 v11, 16, v11
	v_add3_u32 v12, v13, v12, s0
	v_and_or_b32 v11, v12, s1, v11
	v_lshl_or_b32 v12, v49, 11, v48
	v_mov_b32_e32 v13, v15
	v_lshl_add_u64 v[12:13], v[22:23], 0, v[12:13]
	global_store_dwordx2 v[12:13], v[10:11], off
	v_bfe_u32 v10, v6, 16, 1
	v_add3_u32 v6, v6, v10, s0
	v_bfe_u32 v10, v7, 16, 1
	v_lshrrev_b32_e32 v6, 16, v6
	v_add3_u32 v7, v7, v10, s0
	v_and_or_b32 v6, v7, s1, v6
	v_bfe_u32 v7, v8, 16, 1
	v_add3_u32 v7, v8, v7, s0
	v_bfe_u32 v8, v9, 16, 1
	v_lshrrev_b32_e32 v7, 16, v7
	v_add3_u32 v8, v9, v8, s0
	v_and_or_b32 v7, v8, s1, v7
	v_add_co_u32_e32 v8, vcc, 0x8000, v12
	s_nop 0
	s_nop 0
	v_addc_co_u32_e32 v9, vcc, 0, v13, vcc
	s_nop 0
	global_store_dwordx2 v[8:9], v[6:7], off
	s_barrier

.Lp3_nost_10:
	s_cmp_gt_u32 s2, 127
	s_cbranch_scc1 .Lp3_ns_a
	v_lshlrev_b32_e32 v75, 2, v0
	v_add_u32_e32 v77, 0x1000, v75
	v_lshlrev_b32_e32 v80, 3, v0
	v_add_u32_e32 v81, 0x1000, v80
	v_add_u32_e32 v151, 0x2000, v80
	s_add_u32 s62, s2, 0x2000
	s_lshl_b32 s62, s62, 14
	s_add_u32 s4, s70, s62
	s_addc_u32 s5, s71, 0
	s_add_u32 s4, s4, 0x9900000
	s_addc_u32 s5, s5, 0
	global_load_dword v153, v75, s[4:5]
	global_load_dword v155, v75, s[4:5] offset:2048
	global_load_dword v157, v77, s[4:5]
	global_load_dword v159, v77, s[4:5] offset:2048
	global_load_dwordx2 v[136:137], v80, s[42:43]
	global_load_dwordx2 v[138:139], v81, s[42:43]
	global_load_dwordx2 v[142:143], v151, s[42:43]
	s_lshl_b32 s62, s2, 13
	s_add_u32 s4, s58, s62
	s_addc_u32 s5, s59, 0
	global_load_dwordx2 v[144:145], v80, s[4:5]
	global_load_dwordx2 v[146:147], v81, s[4:5]
	s_mul_i32 s62, s2, 0xf000
	s_add_u32 s62, s56, s62
	s_addc_u32 s63, s57, 0
	global_load_dwordx2 v[148:149], v80, s[62:63]
	s_add_u32 s62, s62, 0x1000
	s_addc_u32 s63, s63, 0
	global_load_dwordx2 v[94:95], v80, s[62:63]
	s_add_u32 s62, s62, 0x1000
	s_addc_u32 s63, s63, 0
	global_load_dwordx2 v[96:97], v80, s[62:63]
	s_add_u32 s62, s62, 0x1000
	s_addc_u32 s63, s63, 0
	global_load_dwordx2 v[98:99], v80, s[62:63]
	s_add_u32 s62, s62, 0x1000
	s_addc_u32 s63, s63, 0

.Lp3_nost_11:
	s_cmp_gt_u32 s2, 127
	s_cbranch_scc1 .Lp3_ns_c
	global_load_dwordx2 v[100:101], v80, s[62:63]
	s_add_u32 s62, s62, 0x1000
	s_addc_u32 s63, s63, 0
	global_load_dwordx2 v[102:103], v80, s[62:63]
	s_add_u32 s62, s62, 0x1000
	s_addc_u32 s63, s63, 0
	global_load_dwordx2 v[104:105], v80, s[62:63]
	s_add_u32 s62, s62, 0x1000
	s_addc_u32 s63, s63, 0

.Lp3_nost_12:
	s_cmp_gt_u32 s2, 127
	s_cbranch_scc1 .Lp3_ns_d
	global_load_dwordx2 v[106:107], v80, s[62:63]
	s_add_u32 s62, s62, 0x1000
	s_addc_u32 s63, s63, 0
	global_load_dwordx2 v[108:109], v80, s[62:63]
	s_add_u32 s62, s62, 0x1000
	s_addc_u32 s63, s63, 0
	global_load_dwordx2 v[110:111], v80, s[62:63]
	s_add_u32 s62, s62, 0x1000
	s_addc_u32 s63, s63, 0

.Lp3_nost_13:
	s_cmp_gt_u32 s2, 127
	s_cbranch_scc1 .Lp3_ns_e
	global_load_dwordx2 v[112:113], v80, s[62:63]
	s_add_u32 s62, s62, 0x1000
	s_addc_u32 s63, s63, 0
	global_load_dwordx2 v[114:115], v80, s[62:63]
	s_add_u32 s62, s62, 0x1000
	s_addc_u32 s63, s63, 0
	global_load_dwordx2 v[116:117], v80, s[62:63]
	s_add_u32 s62, s62, 0x1000
	s_addc_u32 s63, s63, 0

.Lp3_nost_14:
	s_cmp_gt_u32 s2, 127
	s_cbranch_scc1 .Lp3_ns_f
	global_load_dwordx2 v[118:119], v80, s[62:63]
	s_add_u32 s62, s62, 0x1000
	s_addc_u32 s63, s63, 0
	global_load_dwordx2 v[120:121], v80, s[62:63]
	s_add_u32 s62, s62, 0x1000
	s_addc_u32 s63, s63, 0

.Lp3_nost_15:
	s_cmp_gt_u32 s2, 127
	s_cbranch_scc1 .Lp3_ns_b
	v_readlane_b32 s62, v255, 5
	s_lshr_b32 s9, s62, 1
	s_add_u32 s7, s9, 1
	s_lshl_b32 s7, s7, 23
	s_sub_u32 s7, 0x3f800000, s7
	s_add_u32 s62, s2, 0x2000
	s_lshl_b32 s62, s62, 11
	s_add_u32 s10, s40, s62
	s_addc_u32 s11, s41, 0
	s_add_u32 s32, s12, s62
	s_addc_u32 s33, s13, 0
	s_mul_i32 s62, s2, 0xf000
	s_add_u32 s88, s30, s62
	s_addc_u32 s89, s31, 0
	s_add_u32 s88, s88, 0x4144000
	s_addc_u32 s89, s89, 0
	s_lshl_b32 s62, s2, 13
	s_add_u32 s90, s30, s62
	s_addc_u32 s91, s31, 0
	s_add_u32 s90, s90, 0x48c4000
	s_addc_u32 s91, s91, 0
	s_waitcnt vmcnt(2)
	v_lshlrev_b32_e32 v248, 16, v153
	v_and_b32_e32 v249, s3, v153
	v_mov_b32_e32 v232, v248
	v_mov_b32_e32 v233, v249
	v_pk_add_f32 v[232:233], v[232:233], v[120:121]
	s_cmp_eq_u32 s9, 0
	s_cbranch_scc1 .Lp3_ss_done
	v_pk_add_f32 v[232:233], v[232:233], v[118:119]
	v_pk_add_f32 v[232:233], v[232:233], v[116:117]
	s_cmp_eq_u32 s9, 1
	s_cbranch_scc1 .Lp3_ss_done
	v_pk_add_f32 v[232:233], v[232:233], v[114:115]
	v_pk_add_f32 v[232:233], v[232:233], v[112:113]
	v_pk_add_f32 v[232:233], v[232:233], v[110:111]
	v_pk_add_f32 v[232:233], v[232:233], v[108:109]
	s_cmp_eq_u32 s9, 2
	s_cbranch_scc1 .Lp3_ss_done
	v_pk_add_f32 v[232:233], v[232:233], v[106:107]
	v_pk_add_f32 v[232:233], v[232:233], v[104:105]
	v_pk_add_f32 v[232:233], v[232:233], v[102:103]
	v_pk_add_f32 v[232:233], v[232:233], v[100:101]
	v_pk_add_f32 v[232:233], v[232:233], v[98:99]
	v_pk_add_f32 v[232:233], v[232:233], v[96:97]
	v_pk_add_f32 v[232:233], v[232:233], v[94:95]
	v_pk_add_f32 v[232:233], v[232:233], v[148:149]
.Lp3_ss_done:
	v_fma_f32 v172, v232, s7, -v248
	v_fma_f32 v173, v233, s7, -v249
	v_cvt_pk_bf16_f32 v172, v172, v173
	global_store_dword v75, v172, s[10:11]
	v_lshlrev_b32_e32 v176, 16, v155
	v_and_b32_e32 v177, s3, v155
	v_lshlrev_b32_e32 v180, 16, v159
	v_and_b32_e32 v181, s3, v159
	v_pk_mul_f32 v[236:237], v[180:181], v[176:177]
	v_pk_mul_f32 v[176:177], v[136:137], v[144:145]
	v_pk_fma_f32 v[176:177], v[138:139], v[146:147], v[176:177]
	v_pk_fma_f32 v[176:177], v[142:143], v[236:237], v[176:177]
	v_lshlrev_b32_e32 v186, 16, v157
	v_and_b32_e32 v187, s3, v157
	v_pk_mul_f32 v[176:177], v[186:187], v[176:177]
	v_cvt_pk_bf16_f32 v176, v176, v177
	global_store_dword v75, v176, s[32:33]
	global_store_dwordx2 v80, v[94:95], s[88:89]
	s_add_u32 s88, s88, 0x1000
	s_addc_u32 s89, s89, 0
	global_store_dwordx2 v80, v[96:97], s[88:89]
	s_add_u32 s88, s88, 0x1000
	s_addc_u32 s89, s89, 0
	global_store_dwordx2 v80, v[98:99], s[88:89]
	s_add_u32 s88, s88, 0x1000
	s_addc_u32 s89, s89, 0
	global_store_dwordx2 v80, v[100:101], s[88:89]
	s_add_u32 s88, s88, 0x1000
	s_addc_u32 s89, s89, 0
	global_store_dwordx2 v80, v[102:103], s[88:89]
	s_add_u32 s88, s88, 0x1000
	s_addc_u32 s89, s89, 0
	global_store_dwordx2 v80, v[104:105], s[88:89]
	s_add_u32 s88, s88, 0x1000
	s_addc_u32 s89, s89, 0
	global_store_dwordx2 v80, v[106:107], s[88:89]
	s_add_u32 s88, s88, 0x1000
	s_addc_u32 s89, s89, 0
	global_store_dwordx2 v80, v[108:109], s[88:89]
	s_add_u32 s88, s88, 0x1000
	s_addc_u32 s89, s89, 0
	global_store_dwordx2 v80, v[110:111], s[88:89]
	s_add_u32 s88, s88, 0x1000
	s_addc_u32 s89, s89, 0
	global_store_dwordx2 v80, v[112:113], s[88:89]
	s_add_u32 s88, s88, 0x1000
	s_addc_u32 s89, s89, 0
	global_store_dwordx2 v80, v[114:115], s[88:89]
	s_add_u32 s88, s88, 0x1000
	s_addc_u32 s89, s89, 0
	global_store_dwordx2 v80, v[116:117], s[88:89]
	s_add_u32 s88, s88, 0x1000
	s_addc_u32 s89, s89, 0
	global_store_dwordx2 v80, v[118:119], s[88:89]
	s_add_u32 s88, s88, 0x1000
	s_addc_u32 s89, s89, 0
	global_store_dwordx2 v80, v[120:121], s[88:89]
	s_add_u32 s88, s88, 0x1000
	s_addc_u32 s89, s89, 0
	global_store_dwordx2 v80, v[248:249], s[88:89]
	global_store_dwordx2 v80, v[146:147], s[90:91]
	global_store_dwordx2 v81, v[236:237], s[90:91]
